# grid barrier 4 (scan to GLA outputs) split into arrive at the end of the scan phase and wait before the first GLA-output item's carried-state loads
# baseline (speedup 1.0000x reference)
; template <bool SAMPLE>
; DI void gla_out(const Params& p, int item, int tbsel, LAS unsigned char* wl, int lane) {
;     unsigned char* ws = p.ws;
;     int b = 0, h, c = 0, t0, sb = 0;
;     if (SAMPLE) { sb = item >> 2; h = item & 3; t0 = T_P + 16 * sb; }
;     else { c = item & 127; const int bh = item >> 7; h = bh & 3; b = bh >> 2; t0 = b * 8192 + 64 * c; }
;     const float* la = (const float*)(ws + OFF_LOGA) + (size_t)t0 * 256 + h * 64 + lane;
;     const bf16_t* qb = (const bf16_t*)(ws + OFF_QB) + (size_t)t0 * 256 + h * 64 + lane;
;     const bf16_t* kb = (const bf16_t*)(ws + OFF_KB) + (size_t)t0 * 256 + h * 64 + lane;
;     LAS unsigned char* Qs = wl; LAS unsigned char* Ks = wl + 9216;
;     float cum = 0.f;
;     constexpr int HB = SAMPLE ? 16 : 32;
;     const int tb = SAMPLE ? 0 : tbsel;
;     const int nhalf = SAMPLE ? 1 : tb + 1;
; #pragma unroll 1
;     for (int hf = 0; hf < nhalf; ++hf) {
;         float lav[HB]; bf16_t qvv[HB], kvv[HB];
; #pragma unroll
;         for (int t = 0; t < HB; ++t) { lav[t] = la[(hf * 32 + t) * 256]; qvv[t] = qb[(hf * 32 + t) * 256]; kvv[t] = kb[(hf * 32 + t) * 256]; }
; #pragma unroll
;         for (int t = 0; t < HB; ++t) {
;             cum += lav[t];
;             const float qv = bf2f(qvv[t]) * __expf(cum), kv = bf2f(kvv[t]) * __expf(-cum);
;             *(LAS bf16_t*)(Qs + (hf * 32 + t) * 144 + 2 * lane) = f2bf(qv);
; DI void xcd_barrier(const XcdBarrier& b) {
;     asm volatile("s_waitcnt vmcnt(0)" ::: "memory");
;     __syncthreads();
;     if (threadIdx.x == 0) {
;         unsigned* bar = b.bar;
;         __builtin_amdgcn_s_waitcnt(0);
;         unsigned nloc = b.st[0], nx = b.st[1];
;         if (nloc == 0u) { xcd_barrier_complete(bar, b.x, nloc, nx); b.st[0] = nloc; b.st[1] = nx; }
;         const unsigned old = xb_add(&bar[XB_XSUB(b.x)], 1u);
;         const unsigned gen = old / nloc;
;         if (old + 1u == (gen + 1u) * nloc) {
;             __builtin_amdgcn_fence(__ATOMIC_RELEASE, "agent");
;             asm volatile("s_waitcnt vmcnt(0)" ::: "memory");
;             const unsigned og = xb_add(&bar[XB_TOP], 1u);
;             const unsigned tg = og / nx;
;             if (og + 1u == (tg + 1u) * nx) xb_add(&bar[XB_TOPGEN], 1u);
;             else XB_SPIN(xb_ld(&bar[XB_TOPGEN]) == tg, bar);
;             __builtin_amdgcn_fence(__ATOMIC_ACQUIRE, "agent");
;             xb_add(&bar[XB_XGEN(b.x)], 1u);
.LBB0_1076:
	s_waitcnt vmcnt(0) lgkmcnt(0)
	s_barrier
	v_cmp_eq_u32_e32 vcc, 0, v203
	s_and_saveexec_b64 s[4:5], vcc
	s_cbranch_execz .Lsb4_arr_done
	v_mov_b32_e32 v0, 0x26100
	ds_read_b32 v1, v0
	ds_read_b32 v2, v0 offset:4
	s_waitcnt lgkmcnt(0)
	s_nop 0
	v_readfirstlane_b32 s6, v1
	v_readfirstlane_b32 s7, v2
	s_lshl_b32 s8, s33, 8
	s_add_u32 s8, s46, s8
	s_addc_u32 s9, s47, 0
	v_mov_b32_e32 v0, 0x1000
	v_mov_b32_e32 v1, 1
	global_atomic_add v2, v0, v1, s[8:9] offset:1024 sc0
	s_mov_b32 s101, 0
	s_waitcnt vmcnt(0)
	v_readfirstlane_b32 s10, v2
	s_mul_i32 s11, s6, 4
	s_add_i32 s10, s10, 1
	s_cmp_eq_u32 s10, s11
	s_cbranch_scc0 .Lsb4_arr_done
	buffer_wbl2 sc1
	s_waitcnt vmcnt(0)
	v_mov_b32_e32 v0, 0x3000
	global_atomic_add v2, v0, v1, s[46:47] offset:1024 sc0
	s_mov_b32 s101, 1
	s_waitcnt vmcnt(0)
	v_readfirstlane_b32 s10, v2
	s_mul_i32 s11, s7, 4
	s_add_i32 s10, s10, 1
	s_cmp_eq_u32 s10, s11
	s_cbranch_scc0 .Lsb4_arr_done
	v_mov_b32_e32 v0, 0x3100
	global_atomic_add v0, v1, s[46:47] offset:1024
	s_mov_b32 s101, 2
.Lsb4_arr_done:
	s_or_b64 exec, exec, s[4:5]
	s_mov_b32 s100, 1
	v_mov_b32_e32 v177, v203
	s_waitcnt lgkmcnt(0)
	s_barrier
	s_nop 0
	v_readfirstlane_b32 s4, v177
	s_ashr_i32 s4, s4, 6
	s_mul_i32 s48, s4, s3
	s_add_i32 s48, s48, s2
	s_cmpk_gt_i32 s48, 0x7ff
	v_and_b32_e32 v190, 63, v177
	s_cbranch_scc1 .LBB0_1139
	v_lshrrev_b32_e32 v1, 5, v190
	v_lshlrev_b32_e32 v0, 2, v1
	v_and_b32_e32 v191, 31, v177
	v_or_b32_e32 v3, 2, v0
	v_cmp_gt_u32_e64 s[8:9], v3, v191
	v_or_b32_e32 v3, 3, v0
	v_cmp_gt_u32_e64 s[10:11], v3, v191
	v_or_b32_e32 v3, 8, v0
	v_cmp_gt_u32_e64 s[12:13], v3, v191
	v_or_b32_e32 v3, 9, v0
	v_cmp_gt_u32_e64 s[14:15], v3, v191
	v_or_b32_e32 v3, 10, v0
	v_cmp_gt_u32_e64 s[16:17], v3, v191
	v_or_b32_e32 v3, 11, v0
	v_cmp_gt_u32_e64 s[18:19], v3, v191
	v_or_b32_e32 v3, 16, v0
	v_cmp_gt_u32_e64 s[20:21], v3, v191
	v_or_b32_e32 v3, 17, v0
	v_cmp_gt_u32_e64 s[22:23], v3, v191
	v_or_b32_e32 v3, 18, v0
	s_load_dwordx4 s[40:43], s[0:1], 0xc0
	s_load_dwordx2 s[38:39], s[0:1], 0x78
	v_cmp_gt_u32_e64 s[24:25], v3, v191
	v_or_b32_e32 v3, 19, v0
	v_cmp_gt_u32_e64 s[26:27], v3, v191
	v_or_b32_e32 v3, 24, v0
	v_cmp_gt_u32_e64 s[28:29], v3, v191
	v_or_b32_e32 v3, 25, v0
	v_lshlrev_b32_e32 v4, 4, v191
	v_mov_b32_e32 v179, 0
	v_cmp_gt_u32_e64 s[30:31], v3, v191
	v_or_b32_e32 v3, 26, v0
	v_lshl_or_b32 v178, v1, 9, v4
	s_mulk_i32 s4, 0x4800
	v_cmp_gt_u32_e64 s[34:35], v3, v191
	v_or_b32_e32 v3, 27, v0
	s_waitcnt lgkmcnt(0)
	v_lshl_add_u64 v[6:7], s[40:41], 0, v[178:179]
	s_mov_b64 s[40:41], 0x2000000
	v_lshlrev_b32_e32 v178, 3, v1
	s_add_i32 s50, s4, 0
	v_lshlrev_b32_e32 v176, 1, v190
	v_lshlrev_b32_e32 v2, 4, v1
	v_cmp_gt_u32_e64 s[36:37], v3, v191
	v_or_b32_e32 v3, 32, v190
	v_lshl_add_u64 v[180:181], v[6:7], 0, s[40:41]
	v_lshl_add_u64 v[6:7], s[42:43], 0, v[178:179]
	v_mov_b32_e32 v5, v179
	v_add_u32_e32 v192, s50, v2
	v_mul_u32_u24_e32 v8, 0x90, v191
	v_mul_u32_u24_e32 v9, 0x90, v3
	v_lshl_add_u64 v[4:5], v[6:7], 0, v[4:5]
	s_mov_b64 s[40:41], 0xa8d0000
	s_add_u32 s52, s42, 0xc9d0000
	v_mov_b32_e32 v3, v179
	v_add_u32_e32 v1, s50, v176
	s_mov_b32 s51, 0
	s_movk_i32 s49, 0x90
	v_cmp_gt_u32_e64 s[4:5], v0, v191
	v_cmp_lt_u32_e64 s[6:7], v0, v191
	v_lshl_add_u64 v[182:183], v[4:5], 0, s[40:41]
	s_addc_u32 s53, s43, 0
	v_lshl_add_u64 v[184:185], s[38:39], 0, v[2:3]
	v_add_u32_e32 v193, 0x2100, v1
	v_lshlrev_b32_e32 v186, 2, v190
	s_mov_b32 s62, 0x9851000
	s_mov_b32 s63, 0xa091000
	s_mov_b32 s64, 0x9852000
	s_mov_b32 s65, 0xa092000
	s_mov_b32 s66, 0x9853000
	s_mov_b32 s67, 0xa093000
	s_mov_b64 s[54:55], 0x8000
	s_mov_b64 s[56:57], 0x4000
	s_movk_i32 s68, 0x1000
	s_movk_i32 s69, 0x2000
	s_movk_i32 s70, 0x3000
	v_add_u32_e32 v194, v192, v8
	v_add_u32_e32 v195, v192, v9
	v_mov_b32_e32 v196, 0x358637bd
	s_mov_b32 s71, 0x800000
	v_lshlrev_b32_e32 v178, 1, v0
	s_mov_b32 s72, s48
	s_branch .LBB0_1131

; template <bool SAMPLE>
; DI void gla_out(const Params& p, int item, int tbsel, LAS unsigned char* wl, int lane) {
;     ...
; #pragma unroll 1
;     for (int hf = 0; hf < nhalf; ++hf) {
;         float lav[HB]; bf16_t qvv[HB], kvv[HB];
; #pragma unroll
;         for (int t = 0; t < HB; ++t) { lav[t] = la[(hf * 32 + t) * 256]; qvv[t] = qb[(hf * 32 + t) * 256]; kvv[t] = kb[(hf * 32 + t) * 256]; }
.LBB0_1132:
	v_lshl_add_u64 v[4:5], s[42:43], 0, v[2:3]
	v_add_co_u32_e64 v12, s[40:41], s62, v4
	v_lshl_add_u64 v[6:7], s[42:43], 0, v[0:1]
	s_nop 0
	v_addc_co_u32_e64 v13, s[40:41], 0, v5, s[40:41]
	v_add_co_u32_e64 v14, s[40:41], s64, v4
	v_add_co_u32_e32 v10, vcc, 0xb950000, v6
	s_nop 0
	v_addc_co_u32_e64 v15, s[40:41], 0, v5, s[40:41]
	v_add_co_u32_e64 v16, s[40:41], s63, v4
	v_addc_co_u32_e32 v11, vcc, 0, v7, vcc
	s_nop 0
	v_addc_co_u32_e64 v17, s[40:41], 0, v5, s[40:41]
	v_add_co_u32_e64 v18, s[40:41], s65, v4
	v_add_co_u32_e32 v24, vcc, 0xb951000, v6
	s_nop 0
	v_addc_co_u32_e64 v19, s[40:41], 0, v5, s[40:41]
	v_add_co_u32_e64 v20, s[40:41], s66, v4
	v_addc_co_u32_e32 v25, vcc, 0, v7, vcc
	s_nop 0
	v_addc_co_u32_e64 v21, s[40:41], 0, v5, s[40:41]
	v_add_co_u32_e64 v22, s[40:41], s67, v4
	s_add_i32 s39, s39, -1
	s_nop 0
	v_addc_co_u32_e64 v23, s[40:41], 0, v5, s[40:41]
	global_load_ushort v26, v[12:13], off offset:512
	global_load_ushort v27, v[16:17], off offset:512
	global_load_ushort v28, v[12:13], off offset:1024
	global_load_ushort v29, v[12:13], off offset:1536
	global_load_ushort v30, v[12:13], off offset:2048
	global_load_ushort v31, v[12:13], off offset:2560
	global_load_ushort v32, v[12:13], off offset:3072
	global_load_ushort v33, v[12:13], off offset:3584
	global_load_ushort v34, v[18:19], off offset:-4096
	global_load_ushort v35, v[14:15], off offset:512
	global_load_ushort v36, v[14:15], off offset:1024
	global_load_ushort v37, v[14:15], off offset:1536
	global_load_ushort v38, v[14:15], off offset:2048
	global_load_ushort v39, v[14:15], off offset:2560
	global_load_ushort v40, v[14:15], off offset:3072
	global_load_ushort v41, v[14:15], off offset:3584
	global_load_ushort v42, v[18:19], off
	global_load_ushort v43, v[18:19], off offset:512
	global_load_ushort v44, v[18:19], off offset:1024
	global_load_ushort v45, v[18:19], off offset:1536
	global_load_ushort v46, v[18:19], off offset:2048
	global_load_ushort v47, v[18:19], off offset:2560
	global_load_ushort v48, v[18:19], off offset:3072
	s_nop 0
	global_load_ushort v18, v[18:19], off offset:3584
	s_nop 0
	global_load_ushort v19, v[16:17], off offset:1024
	global_load_ushort v49, v[16:17], off offset:1536
	global_load_ushort v50, v[16:17], off offset:2048
	global_load_ushort v51, v[16:17], off offset:2560
	global_load_ushort v52, v[16:17], off offset:3072
	s_nop 0
	global_load_ushort v16, v[16:17], off offset:3584
	s_nop 0
	global_load_ushort v17, v[20:21], off
	global_load_ushort v53, v[20:21], off offset:512
	global_load_ushort v54, v[22:23], off
	global_load_ushort v55, v[22:23], off offset:512
	global_load_ushort v56, v[20:21], off offset:1024
	global_load_ushort v57, v[20:21], off offset:1536
	global_load_ushort v58, v[20:21], off offset:2048
	global_load_ushort v59, v[20:21], off offset:2560
	global_load_ushort v60, v[20:21], off offset:3072
	s_nop 0
	global_load_ushort v20, v[20:21], off offset:3584
	s_nop 0
	global_load_ushort v21, v[14:15], off offset:-4096
	global_load_ushort v61, v[14:15], off
	global_load_ushort v62, v[22:23], off offset:1024
	global_load_ushort v63, v[22:23], off offset:1536
	global_load_ushort v64, v[22:23], off offset:2048
	global_load_ushort v65, v[22:23], off offset:2560
	global_load_ushort v66, v[22:23], off offset:3072
	s_nop 0
	global_load_ushort v22, v[22:23], off offset:3584
	v_add_co_u32_e32 v12, vcc, 0xb952000, v6
	global_load_dword v23, v[10:11], off
	global_load_dword v67, v[10:11], off offset:1024
	global_load_dword v68, v[10:11], off offset:2048
	global_load_dword v69, v[10:11], off offset:3072
	global_load_dword v70, v[24:25], off
	global_load_dword v71, v[24:25], off offset:1024
	global_load_dword v72, v[24:25], off offset:2048
	s_nop 0
	global_load_dword v24, v[24:25], off offset:3072
	v_addc_co_u32_e32 v13, vcc, 0, v7, vcc
	v_add_co_u32_e32 v10, vcc, 0xb953000, v6
	v_lshl_add_u64 v[0:1], v[0:1], 0, s[54:55]
	s_nop 0
	v_addc_co_u32_e32 v11, vcc, 0, v7, vcc
	v_add_co_u32_e32 v14, vcc, 0xb954000, v6
	global_load_dword v25, v[12:13], off
	global_load_dword v73, v[12:13], off offset:1024
	global_load_dword v74, v[12:13], off offset:2048
	global_load_dword v75, v[12:13], off offset:3072
	global_load_dword v76, v[10:11], off
	global_load_dword v77, v[10:11], off offset:1024
	global_load_dword v78, v[10:11], off offset:2048
	global_load_dword v79, v[10:11], off offset:3072
	v_addc_co_u32_e32 v15, vcc, 0, v7, vcc
	v_add_co_u32_e32 v10, vcc, 0xb955000, v6
	v_lshl_add_u64 v[2:3], v[2:3], 0, s[56:57]
	s_nop 0
	v_addc_co_u32_e32 v11, vcc, 0, v7, vcc
	v_add_co_u32_e32 v12, vcc, 0xb956000, v6
	global_load_dword v80, v[14:15], off
	global_load_dword v81, v[14:15], off offset:1024
	global_load_dword v82, v[14:15], off offset:2048
	s_nop 0
	global_load_dword v14, v[14:15], off offset:3072
	s_nop 0
	global_load_dword v15, v[10:11], off
	global_load_dword v83, v[10:11], off offset:1024
	global_load_dword v84, v[10:11], off offset:2048
	global_load_dword v85, v[10:11], off offset:3072
	v_addc_co_u32_e32 v13, vcc, 0, v7, vcc
	v_add_co_u32_e32 v6, vcc, 0xb957000, v6
	s_cmp_eq_u32 s39, 0
	s_nop 0
	v_addc_co_u32_e32 v7, vcc, 0, v7, vcc
	v_add_co_u32_e32 v10, vcc, 0x9850000, v4
	global_load_dword v86, v[12:13], off
	global_load_dword v87, v[12:13], off offset:1024
	global_load_dword v88, v[12:13], off offset:2048
	s_nop 0
	global_load_dword v12, v[12:13], off offset:3072
	s_nop 0
	global_load_dword v13, v[6:7], off
	global_load_dword v89, v[6:7], off offset:1024
	global_load_dword v90, v[6:7], off offset:2048
	s_nop 0
	global_load_dword v6, v[6:7], off offset:3072
	v_addc_co_u32_e32 v11, vcc, 0, v5, vcc
	v_add_co_u32_e32 v4, vcc, 0xa090000, v4
	s_waitcnt vmcnt(62)
; #define LAS __attribute__((address_space(3)))
; DI bf16_t f2bf(float a) { return (bf16_t)(pk2(a, 0.f) & 0xffffu); }
; DI float bf2f(bf16_t v) { return __uint_as_float(((unsigned)v) << 16); }
; template <bool SAMPLE>
; DI void gla_out(const Params& p, int item, int tbsel, LAS unsigned char* wl, int lane) {
;     ...
; #pragma unroll
;         for (int t = 0; t < HB; ++t) {
;             cum += lav[t];
;             const float qv = bf2f(qvv[t]) * __expf(cum), kv = bf2f(kvv[t]) * __expf(-cum);
;             *(LAS bf16_t*)(Qs + (hf * 32 + t) * 144 + 2 * lane) = f2bf(qv);
;             *(LAS bf16_t*)(Ks + (hf * 32 + t) * 144 + 2 * lane) = f2bf(kv);
;         }
	v_lshlrev_b32_e32 v26, 16, v26
	v_addc_co_u32_e32 v5, vcc, 0, v5, vcc
	global_load_ushort v7, v[10:11], off
	global_load_ushort v91, v[10:11], off offset:512
	global_load_ushort v92, v[10:11], off offset:1024
	global_load_ushort v93, v[10:11], off offset:1536
	global_load_ushort v94, v[10:11], off offset:2048
	global_load_ushort v95, v[10:11], off offset:2560
	global_load_ushort v96, v[10:11], off offset:3072
	s_nop 0
	global_load_ushort v10, v[10:11], off offset:3584
	s_nop 0
	global_load_ushort v11, v[4:5], off
	global_load_ushort v97, v[4:5], off offset:512
	global_load_ushort v98, v[4:5], off offset:1024
	global_load_ushort v99, v[4:5], off offset:1536
	global_load_ushort v100, v[4:5], off offset:2048
	global_load_ushort v101, v[4:5], off offset:2560
	global_load_ushort v102, v[4:5], off offset:3072
	s_nop 0
	global_load_ushort v4, v[4:5], off offset:3584
	v_lshlrev_b32_e32 v27, 16, v27
	v_lshlrev_b32_e32 v28, 16, v28
	v_lshlrev_b32_e32 v29, 16, v29
	v_lshlrev_b32_e32 v30, 16, v30
	v_lshlrev_b32_e32 v31, 16, v31
	v_lshlrev_b32_e32 v32, 16, v32
	v_lshlrev_b32_e32 v33, 16, v33
	v_lshlrev_b32_e32 v42, 16, v42
	v_lshlrev_b32_e32 v35, 16, v35
	v_lshlrev_b32_e32 v43, 16, v43
	v_lshlrev_b32_e32 v36, 16, v36
	s_waitcnt vmcnt(62)
	v_lshlrev_b32_e32 v44, 16, v44
	v_lshlrev_b32_e32 v37, 16, v37
	v_lshlrev_b32_e32 v45, 16, v45
	v_lshlrev_b32_e32 v38, 16, v38
	v_lshlrev_b32_e32 v19, 16, v19
	v_lshlrev_b32_e32 v46, 16, v46
	v_lshlrev_b32_e32 v39, 16, v39
	v_lshlrev_b32_e32 v47, 16, v47
	v_lshlrev_b32_e32 v40, 16, v40
	v_lshlrev_b32_e32 v16, 16, v16
	v_lshlrev_b32_e32 v48, 16, v48
	v_lshlrev_b32_e32 v41, 16, v41
	v_lshlrev_b32_e32 v18, 16, v18
	v_lshlrev_b32_e32 v17, 16, v17
	v_lshlrev_b32_e32 v54, 16, v54
	v_lshlrev_b32_e32 v53, 16, v53
	v_lshlrev_b32_e32 v55, 16, v55
	s_waitcnt vmcnt(61)
	v_lshlrev_b32_e32 v56, 16, v56
	s_waitcnt vmcnt(60)
	v_lshlrev_b32_e32 v57, 16, v57
	s_waitcnt vmcnt(59)
	v_lshlrev_b32_e32 v58, 16, v58
	s_waitcnt vmcnt(55)
	v_lshlrev_b32_e32 v5, 16, v21
	v_lshlrev_b32_e32 v21, 16, v34
	v_lshlrev_b32_e32 v34, 16, v49
	s_waitcnt vmcnt(47)
	v_add_f32_e32 v9, v9, v23
	v_lshlrev_b32_e32 v49, 16, v50
	v_lshlrev_b32_e32 v50, 16, v51
	v_lshlrev_b32_e32 v51, 16, v52
	v_lshlrev_b32_e32 v52, 16, v61
	v_lshlrev_b32_e32 v61, 16, v62
	v_lshlrev_b32_e32 v62, 16, v63
	v_lshlrev_b32_e32 v63, 16, v64
	v_lshlrev_b32_e32 v64, 16, v65
	v_lshlrev_b32_e32 v65, 16, v66
	v_mul_f32_e32 v23, 0x3fb8aa3b, v9
	v_mul_f32_e32 v66, 0xbfb8aa3b, v9
	s_waitcnt vmcnt(46)
	v_add_f32_e32 v9, v9, v67
	v_mul_f32_e32 v67, 0x3fb8aa3b, v9
	v_mul_f32_e32 v103, 0xbfb8aa3b, v9
	s_waitcnt vmcnt(45)
	v_add_f32_e32 v9, v9, v68
	v_exp_f32_e32 v68, v103
	v_mul_f32_e32 v103, 0x3fb8aa3b, v9
	v_mul_f32_e32 v104, 0xbfb8aa3b, v9
	s_waitcnt vmcnt(44)
	v_add_f32_e32 v9, v9, v69
	v_exp_f32_e32 v69, v103
	v_exp_f32_e32 v103, v104
	v_mul_f32_e32 v104, 0x3fb8aa3b, v9
	v_mul_f32_e32 v105, 0xbfb8aa3b, v9
	s_waitcnt vmcnt(43)
	v_add_f32_e32 v9, v9, v70
	v_exp_f32_e32 v23, v23
	v_exp_f32_e32 v67, v67
	v_exp_f32_e32 v70, v104
	v_exp_f32_e32 v104, v105
	v_mul_f32_e32 v105, 0x3fb8aa3b, v9
	v_mul_f32_e32 v106, 0xbfb8aa3b, v9
	s_waitcnt vmcnt(42)
	v_add_f32_e32 v9, v9, v71
	v_exp_f32_e32 v66, v66
	v_exp_f32_e32 v71, v105
	v_exp_f32_e32 v105, v106
	v_mul_f32_e32 v106, 0x3fb8aa3b, v9
	v_mul_f32_e32 v107, 0xbfb8aa3b, v9
	s_waitcnt vmcnt(41)
	v_add_f32_e32 v9, v9, v72
	v_exp_f32_e32 v72, v106
	v_exp_f32_e32 v106, v107
	v_mul_f32_e32 v107, 0x3fb8aa3b, v9
	v_mul_f32_e32 v108, 0xbfb8aa3b, v9
	s_waitcnt vmcnt(40)
	v_add_f32_e32 v9, v9, v24
	s_waitcnt vmcnt(15)
	v_lshlrev_b32_e32 v7, 16, v7
	s_waitcnt vmcnt(14)
	v_lshlrev_b32_e32 v24, 16, v91
	s_waitcnt vmcnt(13)
	v_lshlrev_b32_e32 v91, 16, v92
	s_waitcnt vmcnt(12)
	v_lshlrev_b32_e32 v92, 16, v93
	s_waitcnt vmcnt(11)
	v_lshlrev_b32_e32 v93, 16, v94
	s_waitcnt vmcnt(10)
	v_lshlrev_b32_e32 v94, 16, v95
	s_waitcnt vmcnt(9)
	v_lshlrev_b32_e32 v95, 16, v96
	v_exp_f32_e32 v96, v107
	v_exp_f32_e32 v107, v108
	v_mul_f32_e32 v108, 0x3fb8aa3b, v9
	v_mul_f32_e32 v109, 0xbfb8aa3b, v9
	v_add_f32_e32 v9, v9, v25
	v_mul_f32_e32 v7, v23, v7
	s_waitcnt vmcnt(7)
	v_lshlrev_b32_e32 v11, 16, v11
	v_mul_f32_e32 v23, v67, v24
	s_waitcnt vmcnt(6)
	v_lshlrev_b32_e32 v24, 16, v97
	v_mul_f32_e32 v25, v69, v91
	s_waitcnt vmcnt(5)
	v_lshlrev_b32_e32 v67, 16, v98
	v_mul_f32_e32 v69, v70, v92
	s_waitcnt vmcnt(4)
	v_lshlrev_b32_e32 v70, 16, v99
	s_waitcnt vmcnt(3)
	v_lshlrev_b32_e32 v91, 16, v100
	s_waitcnt vmcnt(2)
	v_lshlrev_b32_e32 v92, 16, v101
	v_exp_f32_e32 v98, v108
	v_exp_f32_e32 v99, v109
	v_mul_f32_e32 v100, 0x3fb8aa3b, v9
	v_mul_f32_e32 v101, 0xbfb8aa3b, v9
	v_add_f32_e32 v9, v9, v73
	v_mul_f32_e32 v11, v66, v11
	v_cvt_pk_bf16_f32 v7, v7, s0
	v_mul_f32_e32 v24, v68, v24
	v_cvt_pk_bf16_f32 v23, v23, s0
	v_mul_f32_e32 v66, v103, v67
	v_cvt_pk_bf16_f32 v25, v25, s0
	v_mul_f32_e32 v67, v104, v70
	v_cvt_pk_bf16_f32 v68, v69, s0
	v_mul_f32_e32 v69, v71, v93
	v_mul_f32_e32 v70, v105, v91
	v_exp_f32_e32 v71, v100
	v_exp_f32_e32 v73, v101
	v_mul_f32_e32 v91, 0x3fb8aa3b, v9
	v_mul_f32_e32 v93, 0xbfb8aa3b, v9
	v_add_f32_e32 v9, v9, v74
	s_waitcnt vmcnt(1)
	v_lshlrev_b32_e32 v97, 16, v102
	ds_write_b16 v8, v7
	v_cvt_pk_bf16_f32 v7, v11, s0
	ds_write_b16 v8, v23 offset:144
	v_cvt_pk_bf16_f32 v11, v24, s0
	ds_write_b16 v8, v25 offset:288
	v_cvt_pk_bf16_f32 v23, v66, s0
	ds_write_b16 v8, v68 offset:432
	v_cvt_pk_bf16_f32 v24, v67, s0
	v_cvt_pk_bf16_f32 v25, v69, s0
	v_cvt_pk_bf16_f32 v66, v70, s0
	v_mul_f32_e32 v67, v72, v94
	v_mul_f32_e32 v68, v106, v92
	v_exp_f32_e32 v69, v91
	v_exp_f32_e32 v70, v93
	v_mul_f32_e32 v72, 0x3fb8aa3b, v9
	v_mul_f32_e32 v74, 0xbfb8aa3b, v9
	v_add_f32_e32 v9, v9, v75
	v_lshlrev_b32_e32 v10, 16, v10
	s_waitcnt vmcnt(0)
; #define LAS __attribute__((address_space(3)))
; DI bf16_t f2bf(float a) { return (bf16_t)(pk2(a, 0.f) & 0xffffu); }
; DI float bf2f(bf16_t v) { return __uint_as_float(((unsigned)v) << 16); }
; template <bool SAMPLE>
; DI void gla_out(const Params& p, int item, int tbsel, LAS unsigned char* wl, int lane) {
;     ...
; #pragma unroll
;         for (int t = 0; t < HB; ++t) {
;             cum += lav[t];
;             const float qv = bf2f(qvv[t]) * __expf(cum), kv = bf2f(kvv[t]) * __expf(-cum);
;             *(LAS bf16_t*)(Qs + (hf * 32 + t) * 144 + 2 * lane) = f2bf(qv);
;             *(LAS bf16_t*)(Ks + (hf * 32 + t) * 144 + 2 * lane) = f2bf(kv);
;         }
	v_lshlrev_b32_e32 v4, 16, v4
	ds_write_b16 v8, v7 offset:9216
	ds_write_b16 v8, v11 offset:9360
	ds_write_b16 v8, v23 offset:9504
	ds_write_b16 v8, v24 offset:9648
	ds_write_b16 v8, v25 offset:576
	ds_write_b16 v8, v66 offset:9792
	v_cvt_pk_bf16_f32 v7, v67, s0
	v_cvt_pk_bf16_f32 v11, v68, s0
	v_mul_f32_e32 v23, v96, v95
	v_mul_f32_e32 v24, v107, v97
	v_exp_f32_e32 v25, v72
	v_exp_f32_e32 v66, v74
	v_mul_f32_e32 v67, 0x3fb8aa3b, v9
	v_mul_f32_e32 v68, 0xbfb8aa3b, v9
	v_add_f32_e32 v9, v9, v76
	ds_write_b16 v8, v7 offset:720
	ds_write_b16 v8, v11 offset:9936
	v_cvt_pk_bf16_f32 v7, v23, s0
	v_cvt_pk_bf16_f32 v11, v24, s0
	v_mul_f32_e32 v10, v98, v10
	v_mul_f32_e32 v4, v99, v4
	v_exp_f32_e32 v23, v67
	v_exp_f32_e32 v24, v68
	v_mul_f32_e32 v67, 0x3fb8aa3b, v9
	v_mul_f32_e32 v68, 0xbfb8aa3b, v9
	v_add_f32_e32 v9, v9, v77
	ds_write_b16 v8, v7 offset:864
	ds_write_b16 v8, v11 offset:10080
	v_cvt_pk_bf16_f32 v7, v10, s0
	v_cvt_pk_bf16_f32 v4, v4, s0
	v_mul_f32_e32 v5, v71, v5
	v_mul_f32_e32 v10, v73, v21
	v_exp_f32_e32 v11, v67
	v_exp_f32_e32 v21, v68
	v_mul_f32_e32 v67, 0x3fb8aa3b, v9
	v_mul_f32_e32 v68, 0xbfb8aa3b, v9
	v_add_f32_e32 v9, v9, v78
	ds_write_b16 v8, v7 offset:1008
	ds_write_b16 v8, v4 offset:10224
	v_cvt_pk_bf16_f32 v4, v5, s0
	v_cvt_pk_bf16_f32 v5, v10, s0
	v_mul_f32_e32 v7, v69, v26
	v_mul_f32_e32 v10, v70, v27
	v_exp_f32_e32 v26, v67
	v_exp_f32_e32 v27, v68
	v_mul_f32_e32 v67, 0x3fb8aa3b, v9
	v_mul_f32_e32 v68, 0xbfb8aa3b, v9
	v_add_f32_e32 v9, v9, v79
	ds_write_b16 v8, v4 offset:1152
	ds_write_b16 v8, v5 offset:10368
	v_cvt_pk_bf16_f32 v4, v7, s0
	v_cvt_pk_bf16_f32 v5, v10, s0
	v_mul_f32_e32 v7, v25, v28
	v_mul_f32_e32 v10, v66, v19
	v_exp_f32_e32 v19, v67
	v_exp_f32_e32 v25, v68
	v_mul_f32_e32 v28, 0x3fb8aa3b, v9
	v_mul_f32_e32 v66, 0xbfb8aa3b, v9
	v_add_f32_e32 v9, v9, v80
	ds_write_b16 v8, v4 offset:1296
	ds_write_b16 v8, v5 offset:10512
	v_cvt_pk_bf16_f32 v4, v7, s0
	v_cvt_pk_bf16_f32 v5, v10, s0
	v_mul_f32_e32 v7, v23, v29
	v_mul_f32_e32 v10, v24, v34
	v_exp_f32_e32 v23, v28
	v_exp_f32_e32 v24, v66
	v_mul_f32_e32 v28, 0x3fb8aa3b, v9
	v_mul_f32_e32 v29, 0xbfb8aa3b, v9
	v_add_f32_e32 v9, v9, v81
	ds_write_b16 v8, v4 offset:1440
	ds_write_b16 v8, v5 offset:10656
	v_cvt_pk_bf16_f32 v4, v7, s0
	v_cvt_pk_bf16_f32 v5, v10, s0
	v_mul_f32_e32 v7, v11, v30
	v_mul_f32_e32 v10, v21, v49
	v_exp_f32_e32 v11, v28
	v_exp_f32_e32 v21, v29
	v_mul_f32_e32 v28, 0x3fb8aa3b, v9
	v_mul_f32_e32 v29, 0xbfb8aa3b, v9
	v_add_f32_e32 v9, v9, v82
	ds_write_b16 v8, v4 offset:1584
	ds_write_b16 v8, v5 offset:10800
	v_cvt_pk_bf16_f32 v4, v7, s0
	v_cvt_pk_bf16_f32 v5, v10, s0
	v_mul_f32_e32 v7, v26, v31
	v_mul_f32_e32 v10, v27, v50
	v_exp_f32_e32 v26, v28
	v_exp_f32_e32 v27, v29
	v_mul_f32_e32 v28, 0x3fb8aa3b, v9
	v_mul_f32_e32 v29, 0xbfb8aa3b, v9
	v_add_f32_e32 v9, v9, v14
	ds_write_b16 v8, v4 offset:1728
	ds_write_b16 v8, v5 offset:10944
	v_cvt_pk_bf16_f32 v4, v7, s0
	v_cvt_pk_bf16_f32 v5, v10, s0
	v_mul_f32_e32 v7, v19, v32
	v_mul_f32_e32 v10, v25, v51
	v_exp_f32_e32 v14, v28
	v_exp_f32_e32 v19, v29
	v_mul_f32_e32 v25, 0x3fb8aa3b, v9
	v_mul_f32_e32 v28, 0xbfb8aa3b, v9
	v_add_f32_e32 v9, v9, v15
	ds_write_b16 v8, v4 offset:1872
	ds_write_b16 v8, v5 offset:11088
	v_cvt_pk_bf16_f32 v4, v7, s0
	v_cvt_pk_bf16_f32 v5, v10, s0
	v_mul_f32_e32 v7, v23, v33
	v_mul_f32_e32 v10, v24, v16
	v_exp_f32_e32 v15, v25
	v_exp_f32_e32 v16, v28
	v_mul_f32_e32 v23, 0x3fb8aa3b, v9
	v_mul_f32_e32 v24, 0xbfb8aa3b, v9
	v_add_f32_e32 v9, v9, v83
	ds_write_b16 v8, v4 offset:2016
	ds_write_b16 v8, v5 offset:11232
	v_cvt_pk_bf16_f32 v4, v7, s0
	v_cvt_pk_bf16_f32 v5, v10, s0
	v_mul_f32_e32 v7, v11, v52
	v_mul_f32_e32 v10, v21, v42
	v_exp_f32_e32 v11, v23
	v_exp_f32_e32 v21, v24
	v_mul_f32_e32 v23, 0x3fb8aa3b, v9
	v_mul_f32_e32 v24, 0xbfb8aa3b, v9
	v_add_f32_e32 v9, v9, v84
	ds_write_b16 v8, v4 offset:2160
	ds_write_b16 v8, v5 offset:11376
	v_cvt_pk_bf16_f32 v4, v7, s0
	v_cvt_pk_bf16_f32 v5, v10, s0
	v_mul_f32_e32 v7, v26, v35
	v_mul_f32_e32 v10, v27, v43
	v_exp_f32_e32 v23, v23
	v_exp_f32_e32 v24, v24
	v_mul_f32_e32 v25, 0x3fb8aa3b, v9
	v_mul_f32_e32 v26, 0xbfb8aa3b, v9
	v_add_f32_e32 v9, v9, v85
	ds_write_b16 v8, v4 offset:2304
	ds_write_b16 v8, v5 offset:11520
	v_cvt_pk_bf16_f32 v4, v7, s0
	v_cvt_pk_bf16_f32 v5, v10, s0
	v_mul_f32_e32 v7, v14, v36
	v_mul_f32_e32 v10, v19, v44
	v_exp_f32_e32 v14, v25
	v_exp_f32_e32 v19, v26
	v_mul_f32_e32 v25, 0x3fb8aa3b, v9
	v_mul_f32_e32 v26, 0xbfb8aa3b, v9
	v_add_f32_e32 v9, v9, v86
	ds_write_b16 v8, v4 offset:2448
	ds_write_b16 v8, v5 offset:11664
; #define LAS __attribute__((address_space(3)))
; DI bf16_t f2bf(float a) { return (bf16_t)(pk2(a, 0.f) & 0xffffu); }
; DI float bf2f(bf16_t v) { return __uint_as_float(((unsigned)v) << 16); }
; DI unsigned xb_ld(unsigned* p)              { return __hip_atomic_load(p, __ATOMIC_RELAXED, __HIP_MEMORY_SCOPE_AGENT); }
; DI unsigned xb_add(unsigned* p, unsigned v) { return __hip_atomic_fetch_add(p, v, __ATOMIC_RELAXED, __HIP_MEMORY_SCOPE_AGENT); }
; #define XB_SPIN(cond, bar) do { unsigned _sp = 0; while (cond) { __builtin_amdgcn_s_sleep(1); \
;     if ((++_sp & 255u) == 0u) { if (xb_ld(&(bar)[XB_TMO])) break; if (_sp > XB_SPIN_CAP) { atomicAdd(&(bar)[XB_TMO], 1u); break; } } } } while (0)
; template <bool SAMPLE>
; DI void gla_out(const Params& p, int item, int tbsel, LAS unsigned char* wl, int lane) {
;     ...
; #pragma unroll
;         for (int t = 0; t < HB; ++t) {
;             cum += lav[t];
;             const float qv = bf2f(qvv[t]) * __expf(cum), kv = bf2f(kvv[t]) * __expf(-cum);
;             *(LAS bf16_t*)(Qs + (hf * 32 + t) * 144 + 2 * lane) = f2bf(qv);
;             *(LAS bf16_t*)(Ks + (hf * 32 + t) * 144 + 2 * lane) = f2bf(kv);
;         }
; DI void xcd_barrier(const XcdBarrier& b) {
;     ...
;             else XB_SPIN(xb_ld(&bar[XB_TOPGEN]) == tg, bar);
;             __builtin_amdgcn_fence(__ATOMIC_ACQUIRE, "agent");
;             xb_add(&bar[XB_XGEN(b.x)], 1u);
;             asm volatile("s_waitcnt vmcnt(0)" ::: "memory");
;         } else {
;             XB_SPIN(xb_ld(&bar[XB_XGEN(b.x)]) == gen, bar);
;             __builtin_amdgcn_fence(__ATOMIC_ACQUIRE, "agent");
;             asm volatile("s_waitcnt vmcnt(0)" ::: "memory");
	v_cvt_pk_bf16_f32 v4, v7, s0
	v_cvt_pk_bf16_f32 v5, v10, s0
	v_mul_f32_e32 v7, v15, v37
	v_mul_f32_e32 v10, v16, v45
	v_exp_f32_e32 v15, v25
	v_exp_f32_e32 v16, v26
	v_mul_f32_e32 v25, 0x3fb8aa3b, v9
	v_mul_f32_e32 v26, 0xbfb8aa3b, v9
	v_add_f32_e32 v9, v9, v87
	ds_write_b16 v8, v4 offset:2592
	ds_write_b16 v8, v5 offset:11808
	v_cvt_pk_bf16_f32 v4, v7, s0
	v_cvt_pk_bf16_f32 v5, v10, s0
	v_mul_f32_e32 v7, v11, v38
	v_mul_f32_e32 v10, v21, v46
	v_exp_f32_e32 v11, v25
	v_exp_f32_e32 v21, v26
	v_mul_f32_e32 v25, 0x3fb8aa3b, v9
	v_mul_f32_e32 v26, 0xbfb8aa3b, v9
	v_add_f32_e32 v9, v9, v88
	ds_write_b16 v8, v4 offset:2736
	ds_write_b16 v8, v5 offset:11952
	v_cvt_pk_bf16_f32 v4, v7, s0
	v_cvt_pk_bf16_f32 v5, v10, s0
	v_mul_f32_e32 v7, v23, v39
	v_mul_f32_e32 v10, v24, v47
	v_exp_f32_e32 v23, v25
	v_exp_f32_e32 v24, v26
	v_mul_f32_e32 v25, 0x3fb8aa3b, v9
	v_mul_f32_e32 v26, 0xbfb8aa3b, v9
	v_add_f32_e32 v9, v9, v12
	ds_write_b16 v8, v4 offset:2880
	ds_write_b16 v8, v5 offset:12096
	v_cvt_pk_bf16_f32 v4, v7, s0
	v_cvt_pk_bf16_f32 v5, v10, s0
	v_mul_f32_e32 v7, v14, v40
	v_mul_f32_e32 v10, v19, v48
	v_exp_f32_e32 v12, v25
	v_exp_f32_e32 v14, v26
	v_mul_f32_e32 v19, 0x3fb8aa3b, v9
	v_mul_f32_e32 v25, 0xbfb8aa3b, v9
	v_add_f32_e32 v9, v9, v13
	ds_write_b16 v8, v4 offset:3024
	ds_write_b16 v8, v5 offset:12240
	v_cvt_pk_bf16_f32 v4, v7, s0
	v_cvt_pk_bf16_f32 v5, v10, s0
	v_mul_f32_e32 v7, v15, v41
	v_mul_f32_e32 v10, v16, v18
	v_exp_f32_e32 v13, v19
	v_mul_f32_e32 v16, 0x3fb8aa3b, v9
	v_mul_f32_e32 v18, 0xbfb8aa3b, v9
	v_add_f32_e32 v9, v9, v89
	v_exp_f32_e32 v15, v25
	ds_write_b16 v8, v4 offset:3168
	ds_write_b16 v8, v5 offset:12384
	v_cvt_pk_bf16_f32 v4, v7, s0
	v_cvt_pk_bf16_f32 v5, v10, s0
	v_mul_f32_e32 v7, v11, v17
	v_mul_f32_e32 v10, v21, v54
	v_exp_f32_e32 v11, v16
	v_exp_f32_e32 v16, v18
	v_mul_f32_e32 v17, 0x3fb8aa3b, v9
	v_mul_f32_e32 v18, 0xbfb8aa3b, v9
	v_add_f32_e32 v9, v9, v90
	ds_write_b16 v8, v4 offset:3312
	ds_write_b16 v8, v5 offset:12528
	v_cvt_pk_bf16_f32 v4, v7, s0
	v_cvt_pk_bf16_f32 v5, v10, s0
	v_mul_f32_e32 v7, v23, v53
	v_mul_f32_e32 v10, v24, v55
	v_exp_f32_e32 v17, v17
	v_mul_f32_e32 v19, 0x3fb8aa3b, v9
	v_mul_f32_e32 v21, 0xbfb8aa3b, v9
	v_add_f32_e32 v9, v9, v6
	v_exp_f32_e32 v18, v18
	ds_write_b16 v8, v4 offset:3456
	ds_write_b16 v8, v5 offset:12672
	v_cvt_pk_bf16_f32 v4, v7, s0
	v_cvt_pk_bf16_f32 v5, v10, s0
	v_mul_f32_e32 v6, v12, v56
	v_mul_f32_e32 v7, v14, v61
	v_exp_f32_e32 v10, v19
	v_mul_f32_e32 v14, 0x3fb8aa3b, v9
	v_exp_f32_e32 v12, v21
	v_mul_f32_e32 v19, 0xbfb8aa3b, v9
	ds_write_b16 v8, v4 offset:3600
	ds_write_b16 v8, v5 offset:12816
	v_cvt_pk_bf16_f32 v4, v6, s0
	v_mul_f32_e32 v6, v13, v57
	v_exp_f32_e32 v13, v14
	v_lshlrev_b32_e32 v59, 16, v59
	v_cvt_pk_bf16_f32 v5, v7, s0
	v_mul_f32_e32 v7, v15, v62
	v_exp_f32_e32 v14, v19
	ds_write_b16 v8, v4 offset:3744
	ds_write_b16 v8, v5 offset:12960
	v_cvt_pk_bf16_f32 v4, v6, s0
	v_mul_f32_e32 v6, v11, v58
	v_lshlrev_b32_e32 v60, 16, v60
	v_cvt_pk_bf16_f32 v5, v7, s0
	v_mul_f32_e32 v7, v16, v63
	ds_write_b16 v8, v4 offset:3888
	ds_write_b16 v8, v5 offset:13104
	v_cvt_pk_bf16_f32 v4, v6, s0
	v_mul_f32_e32 v6, v17, v59
	v_lshlrev_b32_e32 v20, 16, v20
	v_cvt_pk_bf16_f32 v5, v7, s0
	v_mul_f32_e32 v7, v18, v64
	ds_write_b16 v8, v4 offset:4032
	ds_write_b16 v8, v5 offset:13248
	v_cvt_pk_bf16_f32 v4, v6, s0
	v_mul_f32_e32 v6, v10, v60
	v_lshlrev_b32_e32 v22, 16, v22
	v_cvt_pk_bf16_f32 v5, v7, s0
	v_mul_f32_e32 v7, v12, v65
	ds_write_b16 v8, v4 offset:4176
	ds_write_b16 v8, v5 offset:13392
	v_cvt_pk_bf16_f32 v4, v6, s0
	v_mul_f32_e32 v6, v13, v20
	v_cvt_pk_bf16_f32 v5, v7, s0
	v_mul_f32_e32 v7, v14, v22
	ds_write_b16 v8, v4 offset:4320
	ds_write_b16 v8, v5 offset:13536
	v_cvt_pk_bf16_f32 v4, v6, s0
	v_cvt_pk_bf16_f32 v5, v7, s0
	ds_write_b16 v8, v4 offset:4464
	ds_write_b16 v8, v5 offset:13680
	v_add_u32_e32 v8, 0x1200, v8
	s_cbranch_scc0 .LBB0_1132
	s_cmp_eq_u32 s100, 0
	s_cbranch_scc1 .Lsb4_done
	s_mov_b32 s100, 0
	v_cmp_eq_u32_e32 vcc, 0, v203
	s_and_saveexec_b64 s[40:41], vcc
	s_cbranch_execz .Lsb4_join
	s_lshl_b32 s76, s33, 8
	s_add_u32 s76, s46, s76
	s_addc_u32 s77, s47, 0
	s_mov_b32 s78, 0
	s_cmp_eq_u32 s101, 2
	s_cbranch_scc1 .Lsb4_lead_go
	s_cmp_eq_u32 s101, 1
	s_cbranch_scc1 .Lsb4_lead_wait
	v_mov_b32_e32 v160, 0x2000
.Lsb4_nl:
	global_load_dword v161, v160, s[76:77] offset:1024 sc1
	s_waitcnt vmcnt(0)
	v_readfirstlane_b32 s79, v161
	s_cmp_lg_u32 s79, 3
	s_cbranch_scc1 .Lsb4_acq
	s_add_i32 s78, s78, 1
	s_cmp_lt_u32 s78, 0x800
	s_cbranch_scc0 .Lsb4_acq
	s_sleep 1
	s_branch .Lsb4_nl

; DI unsigned xb_ld(unsigned* p)              { return __hip_atomic_load(p, __ATOMIC_RELAXED, __HIP_MEMORY_SCOPE_AGENT); }
; DI unsigned xb_add(unsigned* p, unsigned v) { return __hip_atomic_fetch_add(p, v, __ATOMIC_RELAXED, __HIP_MEMORY_SCOPE_AGENT); }
; #define XB_SPIN(cond, bar) do { unsigned _sp = 0; while (cond) { __builtin_amdgcn_s_sleep(1); \
;     if ((++_sp & 255u) == 0u) { if (xb_ld(&(bar)[XB_TMO])) break; if (_sp > XB_SPIN_CAP) { atomicAdd(&(bar)[XB_TMO], 1u); break; } } } } while (0)
; DI void xcd_barrier(const XcdBarrier& b) {
;     ...
;             if (og + 1u == (tg + 1u) * nx) xb_add(&bar[XB_TOPGEN], 1u);
;             else XB_SPIN(xb_ld(&bar[XB_TOPGEN]) == tg, bar);
;             __builtin_amdgcn_fence(__ATOMIC_ACQUIRE, "agent");
.Lsb4_lw:
	global_load_dword v161, v160, s[46:47] offset:1024 sc1
	s_waitcnt vmcnt(0)
	v_readfirstlane_b32 s79, v161
	s_cmp_lg_u32 s79, 3
	s_cbranch_scc1 .Lsb4_lead_go
	s_add_i32 s78, s78, 1
	s_cmp_lt_u32 s78, 0x800
	s_cbranch_scc0 .Lsb4_lead_go
	s_sleep 1
	s_branch .Lsb4_lw

; template <bool SAMPLE>
; DI void gla_out(const Params& p, int item, int tbsel, LAS unsigned char* wl, int lane) {
;     ...
;     if (!SAMPLE) {
; #pragma unroll
;         for (int dvb = 0; dvb < 4; ++dvb)
; #pragma unroll
;             for (int kk = 0; kk < 4; ++kk) sa[dvb][kk] = *(const bf16x8*)((const bf16_t*)(p.out + O_SPB) + (size_t)item * 8192 + (size_t)(((dvb * 4 + kk) * 2 + hh) * 32 + qi) * 8);
; #pragma unroll
;         for (int sbk = 0; sbk < 2; ++sbk) if (sbk <= tb) {
; #pragma unroll
;             for (int ks = 0; ks < 2; ++ks)
; #pragma unroll
;                 for (int dvb = 0; dvb < 4; ++dvb) {
;                     const bf16_t* vp = (const bf16_t*)(ws + OFF_VBT) + (size_t)item * 8192 + (size_t)((dvb * 8 + 4 * sbk + 2 * ks) * 32 + qi) * 8 + 4 * hh;
;                     vf[sbk][ks][dvb][0] = *(const u32x2*)vp; vf[sbk][ks][dvb][1] = *(const u32x2*)(vp + 256);
;                 }
;         }
.Lsb4_done:
	s_ashr_i32 s61, s60, 31
	s_lshl_b64 s[40:41], s[60:61], 14
	v_lshl_add_u64 v[32:33], v[180:181], 0, s[40:41]
	v_add_co_u32_e32 v8, vcc, 0x1000, v32
	global_load_dwordx4 v[24:27], v[32:33], off
	global_load_dwordx4 v[16:19], v[32:33], off offset:1024
	global_load_dwordx4 v[4:7], v[32:33], off offset:2048
	global_load_dwordx4 v[0:3], v[32:33], off offset:3072
	v_addc_co_u32_e32 v9, vcc, 0, v33, vcc
	v_add_co_u32_e32 v34, vcc, 0x2000, v32
	global_load_dwordx4 v[28:31], v[8:9], off
	global_load_dwordx4 v[20:23], v[8:9], off offset:1024
	global_load_dwordx4 v[12:15], v[8:9], off offset:2048
	s_nop 0
	global_load_dwordx4 v[8:11], v[8:9], off offset:3072
	v_addc_co_u32_e32 v35, vcc, 0, v33, vcc
	v_add_co_u32_e32 v32, vcc, 0x3000, v32
	global_load_dwordx4 v[144:147], v[34:35], off
	global_load_dwordx4 v[72:75], v[34:35], off offset:1024
	global_load_dwordx4 v[68:71], v[34:35], off offset:2048
	global_load_dwordx4 v[64:67], v[34:35], off offset:3072
	v_addc_co_u32_e32 v33, vcc, 0, v33, vcc
	global_load_dwordx4 v[156:159], v[32:33], off
	global_load_dwordx4 v[152:155], v[32:33], off offset:1024
	global_load_dwordx4 v[148:151], v[32:33], off offset:2048
	global_load_dwordx4 v[76:79], v[32:33], off offset:3072
	v_lshl_add_u64 v[32:33], v[182:183], 0, s[40:41]
	v_add_co_u32_e32 v34, vcc, s68, v32
	s_and_b32 s38, s38, 1
	s_nop 0
	v_addc_co_u32_e32 v35, vcc, 0, v33, vcc
	v_add_co_u32_e32 v36, vcc, s69, v32
	s_cmp_eq_u32 s38, 0
	s_nop 0
	v_addc_co_u32_e32 v37, vcc, 0, v33, vcc
	v_add_co_u32_e32 v38, vcc, s70, v32
	s_cselect_b64 s[60:61], -1, 0
	s_nop 0
	v_addc_co_u32_e32 v39, vcc, 0, v33, vcc
	global_load_dwordx2 v[136:137], v[32:33], off
	global_load_dwordx2 v[138:139], v[32:33], off offset:512
	global_load_dwordx2 v[124:125], v[32:33], off offset:1024
	global_load_dwordx2 v[126:127], v[32:33], off offset:1536
	global_load_dwordx2 v[142:143], v[34:35], off offset:512
	global_load_dwordx2 v[128:129], v[38:39], off
	global_load_dwordx2 v[120:121], v[34:35], off offset:1024
	global_load_dwordx2 v[122:123], v[34:35], off offset:1536
	global_load_dwordx2 v[132:133], v[36:37], off
	global_load_dwordx2 v[134:135], v[36:37], off offset:512
	global_load_dwordx2 v[116:117], v[36:37], off offset:1024
	global_load_dwordx2 v[118:119], v[36:37], off offset:1536
	global_load_dwordx2 v[140:141], v[36:37], off offset:-4096
	global_load_dwordx2 v[130:131], v[38:39], off offset:512
	global_load_dwordx2 v[104:105], v[38:39], off offset:1024
	global_load_dwordx2 v[106:107], v[38:39], off offset:1536
	s_cmp_eq_u32 s38, 1
	s_cselect_b64 s[40:41], -1, 0
	s_and_b64 vcc, exec, s[40:41]
	s_cbranch_vccz .LBB0_1135
	v_add_co_u32_e32 v34, vcc, 0x1000, v32
	s_nop 1
	v_addc_co_u32_e32 v35, vcc, 0, v33, vcc
	v_add_co_u32_e32 v36, vcc, 0x2000, v32
	s_nop 1
	v_addc_co_u32_e32 v37, vcc, 0, v33, vcc
	v_add_co_u32_e32 v38, vcc, 0x3000, v32
	s_nop 1
	v_addc_co_u32_e32 v39, vcc, 0, v33, vcc
	global_load_dwordx2 v[112:113], v[32:33], off offset:2048
	global_load_dwordx2 v[114:115], v[32:33], off offset:2560
	global_load_dwordx2 v[84:85], v[32:33], off offset:3072
	global_load_dwordx2 v[86:87], v[32:33], off offset:3584
	global_load_dwordx2 v[108:109], v[34:35], off offset:2048
	global_load_dwordx2 v[110:111], v[34:35], off offset:2560
	global_load_dwordx2 v[80:81], v[34:35], off offset:3072
	global_load_dwordx2 v[82:83], v[34:35], off offset:3584
	global_load_dwordx2 v[100:101], v[36:37], off offset:2048
	global_load_dwordx2 v[102:103], v[36:37], off offset:2560
	global_load_dwordx2 v[88:89], v[36:37], off offset:3072
	global_load_dwordx2 v[90:91], v[36:37], off offset:3584
	global_load_dwordx2 v[96:97], v[38:39], off offset:2048
	global_load_dwordx2 v[98:99], v[38:39], off offset:2560
	global_load_dwordx2 v[92:93], v[38:39], off offset:3072
	global_load_dwordx2 v[94:95], v[38:39], off offset:3584

; DI unsigned xb_ld(unsigned* p)              { return __hip_atomic_load(p, __ATOMIC_RELAXED, __HIP_MEMORY_SCOPE_AGENT); }
; #define XB_SPIN(cond, bar) do { unsigned _sp = 0; while (cond) { __builtin_amdgcn_s_sleep(1); \
;     if ((++_sp & 255u) == 0u) { if (xb_ld(&(bar)[XB_TMO])) break; if (_sp > XB_SPIN_CAP) { atomicAdd(&(bar)[XB_TMO], 1u); break; } } } } while (0)
; DI void p4_gla_out(const Params& p, LAS unsigned char* lds) {
;     ...
;     if (((gw >> 3) & 1) == 0) for (int it = ((gw >> 4) << 3) | (gw & 7); it < 512; it += NGW >> 1) sample_out_item(p, it, lane);
; DI void xcd_barrier(const XcdBarrier& b) {
;     ...
;             asm volatile("s_waitcnt vmcnt(0)" ::: "memory");
;         } else {
;             XB_SPIN(xb_ld(&bar[XB_XGEN(b.x)]) == gen, bar);
;             __builtin_amdgcn_fence(__ATOMIC_ACQUIRE, "agent");
;             asm volatile("s_waitcnt vmcnt(0)" ::: "memory");
;         }
.LBB0_1139:
	s_cmp_eq_u32 s100, 0
	s_cbranch_scc1 .Lsb4b_done
	s_mov_b32 s100, 0
	v_cmp_eq_u32_e32 vcc, 0, v203
	s_and_saveexec_b64 s[40:41], vcc
	s_cbranch_execz .Lsb4b_join
	s_lshl_b32 s76, s33, 8
	s_add_u32 s76, s46, s76
	s_addc_u32 s77, s47, 0
	s_mov_b32 s78, 0
	s_cmp_eq_u32 s101, 2
	s_cbranch_scc1 .Lsb4b_lead_go
	s_cmp_eq_u32 s101, 1
	s_cbranch_scc1 .Lsb4b_lead_wait
	v_mov_b32_e32 v160, 0x2000

; DI void sample_out_item(const Params& p, int item, int lane) {
;     unsigned char* ws = p.ws;
;     const int qi = lane & 31, hh = lane >> 5, tg = item >> 5, nb = item & 31;
;     const int tok = T_P + 32 * tg + qi, wrow = wt_row(nb) + qi;
;     const bf16_t* up = (const bf16_t*)(ws + OFF_UB) + (size_t)tok * 1024 + 8 * hh;
;     const bf16_t* wp = (const bf16_t*)(ws + OFF_WOUT) + (size_t)wrow * 1024 + 8 * hh;
; DI void p4_gla_out(const Params& p, LAS unsigned char* lds) {
;     ...
;     if (((gw >> 3) & 1) == 0) for (int it = ((gw >> 4) << 3) | (gw & 7); it < 512; it += NGW >> 1) sample_out_item(p, it, lane);
.Lsb4b_join:
	s_or_b64 exec, exec, s[40:41]
	s_barrier
.Lsb4b_done:
	s_bitcmp0_b32 s48, 3
	s_cbranch_scc0 .LBB0_1145
	s_ashr_i32 s10, s48, 1
	s_and_b32 s4, s10, -8
	s_and_b32 s11, s48, 7
	s_or_b32 s16, s4, s11
	s_cmpk_gt_i32 s16, 0x1ff
	s_cbranch_scc1 .LBB0_1145
	s_load_dwordx4 s[4:7], s[0:1], 0xc0
	s_load_dwordx2 s[8:9], s[0:1], 0x8
	v_lshrrev_b32_e32 v0, 3, v190
	v_and_b32_e32 v1, 31, v177
	v_and_b32_e32 v0, 4, v0
	v_mov_b32_e32 v17, 0
	v_lshrrev_b32_e32 v2, 1, v177
	s_and_b32 s12, s48, 1
	s_and_b32 s10, s10, 24
	s_brev_b32 s14, 63
	v_or_b32_e32 v28, 0x4000, v1
	s_lshl_b32 s17, s3, 2
	v_and_b32_e32 v18, 16, v2
	v_mov_b32_e32 v19, v17
	v_lshl_or_b32 v29, s12, 7, v1
	s_or_b32 s18, s10, s11
	s_mov_b32 s19, 0x1100000
	s_mov_b32 s11, 0
	s_mov_b32 s20, 0x5700000
	s_mov_b64 s[12:13], 0x200
	v_lshlrev_b32_e32 v20, 2, v0
	s_mov_b32 s15, -1
